# combo2 + ph0 Kmat wave-items moved to waves 4-7
# baseline (speedup 1.0000x reference)
; __device__ __forceinline__ void s5_build(const Frame& F, const S5P& P, bf16* W1T, bf16* WYT, float* KMAT) {
;     const int it0 = F.gw * 64 + F.lane, NT = F.NGW * 64;
;     for (int it = F.gw; it < 32 * 32; it += F.NGW) { const int g = it >> 5, j = it & 31; const float delta = expf(P.lstep[g]);
;         const float lr = P.lre[g * 64 + F.lane], li = P.lim[g * 64 + F.lane]; float pr, pi, cr, ci; cpow(lr, li, delta, (float)j, pr, pi); s5_coef(lr, li, delta, cr, ci);
.LBB0_5:
	s_or_b64 exec, exec, s[4:5]
	s_cmp_lt_i32 s80, 1
	s_cselect_b64 s[0:1], -1, 0
	s_cmp_gt_i32 s81, 0
	s_cselect_b64 s[2:3], -1, 0
	s_and_b64 s[0:1], s[0:1], s[2:3]
	s_andn2_b64 vcc, exec, s[0:1]
	v_writelane_b32 v254, s74, 3
	s_nop 1
	v_writelane_b32 v254, s75, 4
	s_cbranch_vccnz .LBB0_187
	v_mov_b32_e32 v14, v0
	s_load_dwordx2 s[28:29], s[74:75], 0xf0
	s_load_dwordx8 s[12:19], s[74:75], 0x38
	s_load_dwordx4 s[20:23], s[74:75], 0x58
	s_load_dwordx2 s[4:5], s[74:75], 0x70
	v_readfirstlane_b32 s0, v14
	s_ashr_i32 s39, s0, 6
	s_mul_i32 s38, s39, s82
	v_and_b32_e32 v34, 63, v14
	s_add_i32 s40, s38, s96
	s_cmpk_lt_i32 s40, 0x400
	v_lshrrev_b32_e32 v35, 2, v34
	v_lshlrev_b32_e32 v36, 4, v34
	s_cbranch_scc1 .LBB0_11
	v_mbcnt_lo_u32_b32 v1, -1, 0
	v_and_b32_e32 v16, 48, v36
	v_mov_b32_e32 v17, 0
	v_mbcnt_hi_u32_b32 v4, -1, v1
	s_waitcnt lgkmcnt(0)
	v_lshl_add_u64 v[2:3], s[28:29], 0, v[16:17]
	s_mov_b64 s[2:3], 0x200000
	v_lshl_add_u64 v[18:19], v[2:3], 0, s[2:3]
	v_lshlrev_b32_e32 v2, 2, v4
	v_and_b32_e32 v20, 0x100, v2
	v_and_b32_e32 v2, 3, v14
	v_mov_b32_e32 v3, 0x100
	v_lshl_or_b32 v16, v2, 4, v3
	s_mov_b32 s8, 0x6dc9c883
	s_lshl_b32 s0, s82, 3
	v_lshlrev_b32_e32 v1, 6, v35
	v_lshl_add_u64 v[22:23], s[16:17], 0, v[16:17]
	v_lshl_add_u64 v[24:25], s[18:19], 0, v[16:17]
	s_mov_b32 s1, 0x3fb8aa3b
	s_mov_b32 s2, 0xc2ce8ed0
	s_mov_b32 s3, 0x42b17218
	v_mov_b32_e32 v15, 0x7f800000
	s_mov_b32 s9, 0x3fc45f30
	s_mov_b64 s[10:11], 0x200
	s_sub_i32 s30, s40, 0x400
